# s20 + p0_wt_nowb: all P0 stores written through and the leader's L2 write-back at barrier 0 dropped
# baseline (speedup 1.0000x reference)
.LBB0_25:
	v_lshl_add_u64 v[40:41], v[18:19], 0, s[0:1]
	global_load_dword v54, v[40:41], off
	v_add_co_u32_e32 v42, vcc, s11, v40
	v_add_u32_e32 v39, v37, v38
	s_nop 0
	v_addc_co_u32_e32 v43, vcc, 0, v41, vcc
	v_add_co_u32_e32 v44, vcc, s12, v40
	v_and_b32_e32 v39, 0x7f, v39
	s_nop 0
	v_addc_co_u32_e32 v45, vcc, 0, v41, vcc
	v_add_co_u32_e32 v46, vcc, s13, v40
	v_lshl_add_u32 v39, v39, 2, s10
	s_nop 0
	v_addc_co_u32_e32 v47, vcc, 0, v41, vcc
	v_add_co_u32_e32 v48, vcc, s14, v40
	s_add_u32 s0, s0, 0x20000
	s_nop 0
	v_addc_co_u32_e32 v49, vcc, 0, v41, vcc
	global_load_dword v42, v[42:43], off
	s_nop 0
	global_load_dword v43, v[44:45], off
	s_nop 0
	global_load_dword v44, v[46:47], off
	global_load_dword v45, v[48:49], off
	v_add_co_u32_e32 v50, vcc, s15, v40
	s_addc_u32 s1, s1, 0
	s_nop 0
	v_addc_co_u32_e32 v51, vcc, 0, v41, vcc
	v_add_co_u32_e32 v52, vcc, s18, v40
	s_cmp_eq_u32 s0, 0x80000
	s_nop 0
	v_addc_co_u32_e32 v53, vcc, 0, v41, vcc
	v_add_co_u32_e32 v40, vcc, s19, v40
	s_nop 1
	v_addc_co_u32_e32 v41, vcc, 0, v41, vcc
	global_load_dword v46, v[50:51], off
	global_load_dword v47, v[52:53], off
	global_load_dword v48, v[40:41], off
	ds_read2st64_b32 v[40:41], v39 offset1:2
	v_add_u32_e32 v39, v36, v38
	v_and_b32_e32 v39, 0x7f, v39
	v_lshl_add_u32 v39, v39, 2, s10
	s_waitcnt vmcnt(7) lgkmcnt(0)
	v_mfma_f32_16x16x4_f32 v[2:5], v54, v40, v[2:5]
	v_mfma_f32_16x16x4_f32 v[6:9], v54, v41, v[6:9]
	ds_read2st64_b32 v[40:41], v39 offset1:2
	v_add_u32_e32 v39, v35, v38
	v_and_b32_e32 v39, 0x7f, v39
	v_lshl_add_u32 v39, v39, 2, s10
	s_waitcnt vmcnt(6) lgkmcnt(0)
	v_mfma_f32_16x16x4_f32 v[2:5], v42, v40, v[2:5]
	v_mfma_f32_16x16x4_f32 v[6:9], v42, v41, v[6:9]
	ds_read2st64_b32 v[40:41], v39 offset1:2
	v_add_u32_e32 v39, v34, v38
	v_and_b32_e32 v39, 0x7f, v39
	v_lshl_add_u32 v39, v39, 2, s10
	s_waitcnt vmcnt(5) lgkmcnt(0)
	v_mfma_f32_16x16x4_f32 v[2:5], v43, v40, v[2:5]
	v_mfma_f32_16x16x4_f32 v[6:9], v43, v41, v[6:9]
	ds_read2st64_b32 v[40:41], v39 offset1:2
	v_add_u32_e32 v39, v33, v38
	v_and_b32_e32 v39, 0x7f, v39
	v_lshl_add_u32 v39, v39, 2, s10
	s_waitcnt vmcnt(4) lgkmcnt(0)
	v_mfma_f32_16x16x4_f32 v[2:5], v44, v40, v[2:5]
	v_mfma_f32_16x16x4_f32 v[6:9], v44, v41, v[6:9]
	ds_read2st64_b32 v[40:41], v39 offset1:2
	v_add_u32_e32 v39, v32, v38
	v_and_b32_e32 v39, 0x7f, v39
	v_lshl_add_u32 v39, v39, 2, s10
	s_waitcnt vmcnt(3) lgkmcnt(0)
	v_mfma_f32_16x16x4_f32 v[2:5], v45, v40, v[2:5]
	v_mfma_f32_16x16x4_f32 v[6:9], v45, v41, v[6:9]
	ds_read2st64_b32 v[40:41], v39 offset1:2
	v_add_u32_e32 v39, v31, v38
	v_and_b32_e32 v39, 0x7f, v39
	v_lshl_add_u32 v39, v39, 2, s10
	s_waitcnt vmcnt(2) lgkmcnt(0)
	v_mfma_f32_16x16x4_f32 v[2:5], v46, v40, v[2:5]
	v_mfma_f32_16x16x4_f32 v[6:9], v46, v41, v[6:9]
	ds_read2st64_b32 v[40:41], v39 offset1:2
	v_add_u32_e32 v39, v12, v38
	v_and_b32_e32 v39, 0x7f, v39
	v_lshl_add_u32 v39, v39, 2, s10
	v_add_u32_e32 v38, v38, v30
	s_waitcnt vmcnt(1) lgkmcnt(0)
	v_mfma_f32_16x16x4_f32 v[2:5], v47, v40, v[2:5]
	v_mfma_f32_16x16x4_f32 v[6:9], v47, v41, v[6:9]
	ds_read2st64_b32 v[40:41], v39 offset1:2
	s_waitcnt vmcnt(0) lgkmcnt(0)
	v_mfma_f32_16x16x4_f32 v[2:5], v48, v40, v[2:5]
	v_mfma_f32_16x16x4_f32 v[6:9], v48, v41, v[6:9]
	s_cbranch_scc0 .LBB0_25
	s_lshl_b32 s0, s16, 13
	s_and_b32 s0, s0, 0x3f0000
	v_lshl_or_b32 v12, v11, 1, s0
	v_readlane_b32 s0, v255, 3
	v_readlane_b32 s1, v255, 4
	s_nop 2
	v_mul_f32_e32 v2, 0x3db504f3, v2
	v_mul_f32_e32 v6, 0x3db504f3, v6
	v_lshl_add_u64 v[18:19], s[0:1], 0, v[12:13]
	s_lshl_b32 s0, s16, 5
	v_bitop3_b32 v12, s0, v29, v28 bitop3:0xc8
	v_lshl_or_b32 v30, s24, 8, v12
	v_bfe_u32 v12, v2, 16, 1
	v_ashrrev_i32_e32 v31, 31, v30
	v_add3_u32 v2, v2, v12, s20
	v_bfe_u32 v12, v6, 16, 1
	v_lshl_add_u64 v[18:19], v[30:31], 1, v[18:19]
	v_lshrrev_b32_e32 v2, 16, v2
	v_add3_u32 v6, v6, v12, s20
	v_lshl_add_u64 v[18:19], v[18:19], 0, v[16:17]
	v_and_or_b32 v2, v6, s21, v2
	global_store_dword v[18:19], v2, off offset:1024 sc1
	v_mul_f32_e32 v2, 0x3db504f3, v3
	v_mul_f32_e32 v3, 0x3db504f3, v7
	v_bfe_u32 v6, v2, 16, 1
	v_add3_u32 v2, v2, v6, s20
	v_bfe_u32 v6, v3, 16, 1
	v_lshrrev_b32_e32 v2, 16, v2
	v_add3_u32 v3, v3, v6, s20
	v_and_or_b32 v6, v3, s21, v2
	v_add_co_u32_e32 v2, vcc, s22, v18
	s_add_i32 s16, s16, s17
	s_nop 0
	v_addc_co_u32_e32 v3, vcc, 0, v19, vcc
	global_store_dword v[2:3], v6, off offset:1024 sc1
	v_mul_f32_e32 v2, 0x3db504f3, v4
	v_mul_f32_e32 v3, 0x3db504f3, v8
	v_bfe_u32 v4, v2, 16, 1
	v_add3_u32 v2, v2, v4, s20
	v_bfe_u32 v4, v3, 16, 1
	v_lshrrev_b32_e32 v2, 16, v2
	v_add3_u32 v3, v3, v4, s20
	v_and_or_b32 v4, v3, s21, v2
	v_add_co_u32_e32 v2, vcc, s23, v18
	s_add_i32 s6, s6, s7
	s_nop 0
	v_addc_co_u32_e32 v3, vcc, 0, v19, vcc
	global_store_dword v[2:3], v4, off offset:1024 sc1
	v_mul_f32_e32 v2, 0x3db504f3, v5
	v_mul_f32_e32 v3, 0x3db504f3, v9
	v_bfe_u32 v4, v2, 16, 1
	v_add3_u32 v2, v2, v4, s20
	v_bfe_u32 v4, v3, 16, 1
	v_lshrrev_b32_e32 v2, 16, v2
	v_add3_u32 v3, v3, v4, s20
	v_and_or_b32 v4, v3, s21, v2
	v_add_co_u32_e32 v2, vcc, 0x3000, v18
	s_add_i32 s8, s8, s9
	s_nop 0
	v_addc_co_u32_e32 v3, vcc, 0, v19, vcc
	s_cmpk_gt_i32 s16, 0x7ff
	global_store_dword v[2:3], v4, off offset:1024 sc1
	s_cbranch_scc0 .LBB0_24

.LBB0_30:
	v_cmp_lt_i32_e64 s[0:1], s9, v2
	v_lshrrev_b32_e32 v3, 4, v2
	s_and_saveexec_b64 s[14:15], s[0:1]
	s_xor_b64 s[14:15], exec, s[14:15]
	s_cbranch_execz .LBB0_32
	v_add_u32_e32 v6, 0xffffe000, v2
	v_and_b32_e32 v8, 6, v2
	v_lshrrev_b32_e32 v9, 8, v6
	v_bfe_u32 v10, v2, 4, 3
	v_and_or_b32 v3, v3, s16, v8
	v_and_or_b32 v9, v9, 56, v10
	v_lshrrev_b32_e32 v3, 1, v3
	v_mul_u32_u24_e32 v3, v9, v3
	v_and_b32_e32 v3, 63, v3
	v_cvt_f32_ubyte0_e32 v3, v3
	v_mul_f32_e32 v3, 0x3c800000, v3
	v_cos_f32_e32 v8, v3
	v_sin_f32_e32 v3, v3
	v_and_b32_e32 v9, 8, v2
	v_cmp_eq_u32_e64 s[0:1], 0, v9
	v_cndmask_b32_e32 v10, v3, v8, vcc
	v_cndmask_b32_e64 v3, v8, -v3, vcc
	v_cndmask_b32_e64 v3, v3, v10, s[0:1]
	v_bfe_u32 v8, v3, 16, 1
	v_add3_u32 v3, v3, v8, s17
	v_lshl_add_u64 v[8:9], v[6:7], 1, s[26:27]
	global_store_short_d16_hi v[8:9], v3, off sc1
.LBB0_32:
	s_andn2_saveexec_b64 s[14:15], s[14:15]
	s_cbranch_execz .LBB0_29
	v_bfe_u32 v6, v2, 3, 4
	v_lshrrev_b32_e32 v8, 7, v2
	v_and_or_b32 v6, v8, 48, v6
	v_and_or_b32 v3, v3, 56, v1
	v_mul_u32_u24_e32 v3, v6, v3
	v_and_b32_e32 v3, 63, v3
	v_cvt_f32_ubyte0_e32 v3, v3
	v_mul_f32_e32 v3, 0x3c800000, v3
	v_sin_f32_e64 v6, -v3
	v_cos_f32_e32 v3, v3
	v_and_b32_e32 v8, 0x400, v2
	v_cmp_eq_u32_e64 s[0:1], 0, v8
	s_nop 1
	v_cndmask_b32_e64 v3, v6, v3, s[0:1]
	v_bfe_u32 v6, v3, 16, 1
	v_add3_u32 v3, v3, v6, s17
	global_store_short_d16_hi v[4:5], v3, off sc1
	s_branch .LBB0_29

.Lxb0_ok:
	s_mov_b32 s32, 0
	v_readlane_b32 s8, v3, 16
	s_bcnt1_i32_b32 s8, s8
	s_cmp_lg_u32 s8, 1
	s_cselect_b32 s8, 1, 0
	s_or_b32 s32, s32, s8
	v_readlane_b32 s8, v3, 17
	s_bcnt1_i32_b32 s8, s8
	s_cmp_lg_u32 s8, 1
	s_cselect_b32 s8, 1, 0
	s_or_b32 s32, s32, s8
	v_readlane_b32 s8, v3, 18
	s_bcnt1_i32_b32 s8, s8
	s_cmp_lg_u32 s8, 1
	s_cselect_b32 s8, 1, 0
	s_or_b32 s32, s32, s8
	v_readlane_b32 s8, v3, 19
	s_bcnt1_i32_b32 s8, s8
	s_cmp_lg_u32 s8, 1
	s_cselect_b32 s8, 1, 0
	s_or_b32 s32, s32, s8
	v_readlane_b32 s8, v3, 20
	s_bcnt1_i32_b32 s8, s8
	s_cmp_lg_u32 s8, 1
	s_cselect_b32 s8, 1, 0
	s_or_b32 s32, s32, s8
	v_readlane_b32 s8, v3, 21
	s_bcnt1_i32_b32 s8, s8
	s_cmp_lg_u32 s8, 1
	s_cselect_b32 s8, 1, 0
	s_or_b32 s32, s32, s8
	v_readlane_b32 s8, v3, 22
	s_bcnt1_i32_b32 s8, s8
	s_cmp_lg_u32 s8, 1
	s_cselect_b32 s8, 1, 0
	s_or_b32 s32, s32, s8
	v_readlane_b32 s8, v3, 23
	s_bcnt1_i32_b32 s8, s8
	s_cmp_lg_u32 s8, 1
	s_cselect_b32 s8, 1, 0
	s_or_b32 s32, s32, s8
	s_cmp_lg_u32 s3, 0x100
	s_cselect_b32 s8, 1, 0
	s_or_b32 s32, s32, s8
	v_writelane_b32 v255, s32, 63
	s_mov_b64 exec, 0xffff
	v_cmp_ne_u32_e32 vcc, 0, v3
	s_nop 3
	v_readlane_b32 s16, v3, s87
	s_bcnt1_i32_b64 s9, vcc
	s_max_u32 s16, s16, 1
	s_max_u32 s9, s9, 1
	s_mov_b64 exec, 1
	v_mov_b32_e32 v1, 0x23ff0
	v_mov_b32_e32 v2, s16
	v_mov_b32_e32 v3, s9
	ds_write_b32 v1, v2
	ds_write_b32 v1, v3 offset:4
	s_waitcnt lgkmcnt(0)
	v_mov_b32_e32 v1, 0x23ff0
	ds_read_b32 v2, v1
	ds_read_b32 v3, v1 offset:4
	s_add_u32 s6, s80, 0x2380000
	s_addc_u32 s7, s81, 0
	s_lshl_b32 s8, s87, 8
	s_add_i32 s9, s8, 0x1400
	s_add_i32 s8, s8, 0x2400
	v_mov_b32_e32 v4, s9
	v_mov_b32_e32 v5, 1
	global_atomic_add v6, v4, v5, s[6:7] sc0
	buffer_inv sc1
	s_waitcnt vmcnt(0) lgkmcnt(0)
	v_readfirstlane_b32 s10, v6
	v_readfirstlane_b32 s11, v2
	v_readfirstlane_b32 s16, v3
	s_add_i32 s10, s10, 1
	s_mul_i32 s11, s11, 1
	s_cmp_lg_u32 s10, s11
	s_cbranch_scc1 .Lxb_nl_0
	v_mov_b32_e32 v4, 0x3400
	global_atomic_add v6, v4, v5, s[6:7] sc0
	s_waitcnt vmcnt(0)
	v_readfirstlane_b32 s10, v6
	s_add_i32 s10, s10, 1
	s_mul_i32 s16, s16, 1
	s_cmp_lg_u32 s10, s16
	s_cbranch_scc1 .Lxb_nl_0
	v_mov_b32_e32 v4, 0x2400
	global_atomic_add v4, v5, s[6:7]
	global_atomic_add v4, v5, s[6:7] offset:256
	global_atomic_add v4, v5, s[6:7] offset:512
	global_atomic_add v4, v5, s[6:7] offset:768
	global_atomic_add v4, v5, s[6:7] offset:1024
	global_atomic_add v4, v5, s[6:7] offset:1280
	global_atomic_add v4, v5, s[6:7] offset:1536
	global_atomic_add v4, v5, s[6:7] offset:1792
	global_atomic_add v4, v5, s[6:7] offset:2048
	global_atomic_add v4, v5, s[6:7] offset:2304
	global_atomic_add v4, v5, s[6:7] offset:2560
	global_atomic_add v4, v5, s[6:7] offset:2816
	global_atomic_add v4, v5, s[6:7] offset:3072
	global_atomic_add v4, v5, s[6:7] offset:3328
	global_atomic_add v4, v5, s[6:7] offset:3584
	global_atomic_add v4, v5, s[6:7] offset:3840
	s_branch .Lxb_done_0
